# speedup vs baseline: 1.0089x; 1.0089x over previous
; #define WAIT_V0() asm volatile("s_waitcnt vmcnt(0)" ::: "memory")
; DEVI void gemm_phase(int TID_, int BID_, const u16* __restrict__ A, const u16* __restrict__ Bt, int K, int nN, int epi, u16* Cb, int ldc,
;                      float* Cf, const float* resid, char* shm) {
;     ...
;     for (int t = 0; t < nkt; ++t) {
;       const int cur = t & 1;
;       const char* sa_ = shm + cur * STAGE_B + a_lds + 1024;
;       const char* sb_ = shm + cur * STAGE_B + b_lds + 1024;
; #pragma unroll
;       for (int m = 0; m < 8; ++m) {
; #pragma unroll
;         for (int n = 0; n < 4; ++n) acc[m][n] = __builtin_amdgcn_mfma_f32_16x16x32_bf16(Bf0[n], At0[m], acc[m][n], 0, 0, 0);
;         At1[m] = *(const bf16x8*)(sa_ + m * 2048);
;         if (m >= 4) Bf1[m - 4] = *(const bf16x8*)(sb_ + (m - 4) * 2048);
;         __builtin_amdgcn_sched_barrier(0);
;       }
;       __builtin_amdgcn_sched_barrier(0);
;       WAIT_V0();
;       asm volatile("s_waitcnt lgkmcnt(0)" ::: "memory");
;       __builtin_amdgcn_s_barrier();
;       asm volatile("" ::: "memory");
;       if (t + 2 < nkt) GLDS_STAGE(cur, t + 2);
;       __builtin_amdgcn_sched_barrier(0);
;       const char* na_ = shm + (cur ^ 1) * STAGE_B + a_lds;
;       const char* nb_ = shm + (cur ^ 1) * STAGE_B + b_lds;
; #pragma unroll
;       for (int m = 0; m < 8; ++m) {
; #pragma unroll
;         for (int n = 0; n < 4; ++n) acc[m][n] = __builtin_amdgcn_mfma_f32_16x16x32_bf16(Bf1[n], At1[m], acc[m][n], 0, 0, 0);
;         At0[m] = *(const bf16x8*)(na_ + m * 2048);
;         if (m >= 4) Bf0[m - 4] = *(const bf16x8*)(nb_ + (m - 4) * 2048);
;         __builtin_amdgcn_sched_barrier(0);
;       }
;       __builtin_amdgcn_sched_barrier(0);
;     }
.Lg_ld:
	v_readfirstlane_b32 s46, v199
	s_nop 3
	s_lshl_b32 s46, s46, 1
	s_add_u32 s44, s20, s22
	s_addc_u32 s45, s21, s23
	s_add_u32 s60, s18, s22
	s_addc_u32 s61, s19, s23
	s_add_i32 s43, s46, s42
	v_add_u32_e32 v188, s42, v233
	v_or_b32_e32 v192, s42, v232
.Lg_ld_A:
	s_waitcnt lgkmcnt(0)
	s_mov_b32 m0, s43
	v_mfma_f32_16x16x32_bf16 v[124:127], v[128:131], v[172:175], v[124:127]
	global_load_lds_dwordx4 v237, s[44:45]
	v_mfma_f32_16x16x32_bf16 v[120:123], v[132:135], v[172:175], v[120:123]
	v_mfma_f32_16x16x32_bf16 v[116:119], v[136:139], v[172:175], v[116:119]
	v_mfma_f32_16x16x32_bf16 v[112:115], v[140:143], v[172:175], v[112:115]
	ds_read_b128 v[172:175], v188 offset:1024
	v_mfma_f32_16x16x32_bf16 v[108:111], v[128:131], v[168:171], v[108:111]
	v_mfma_f32_16x16x32_bf16 v[104:107], v[132:135], v[168:171], v[104:107]
	v_mfma_f32_16x16x32_bf16 v[100:103], v[136:139], v[168:171], v[100:103]
	v_mfma_f32_16x16x32_bf16 v[96:99], v[140:143], v[168:171], v[96:99]
	ds_read_b128 v[168:171], v188 offset:3072
	s_add_u32 m0, s43, 0x4000
	v_mfma_f32_16x16x32_bf16 v[92:95], v[128:131], v[164:167], v[92:95]
	global_load_lds_dwordx4 v238, s[44:45]
	v_mfma_f32_16x16x32_bf16 v[88:91], v[132:135], v[164:167], v[88:91]
	v_mfma_f32_16x16x32_bf16 v[84:87], v[136:139], v[164:167], v[84:87]
	v_mfma_f32_16x16x32_bf16 v[80:83], v[140:143], v[164:167], v[80:83]
	ds_read_b128 v[164:167], v188 offset:5120
	v_mfma_f32_16x16x32_bf16 v[76:79], v[128:131], v[160:163], v[76:79]
	v_mfma_f32_16x16x32_bf16 v[72:75], v[132:135], v[160:163], v[72:75]
	v_mfma_f32_16x16x32_bf16 v[68:71], v[136:139], v[160:163], v[68:71]
	v_mfma_f32_16x16x32_bf16 v[56:59], v[140:143], v[160:163], v[56:59]
	ds_read_b128 v[160:163], v188 offset:7168
	s_add_u32 m0, s43, 0x8000
	v_mfma_f32_16x16x32_bf16 v[28:31], v[128:131], v[156:159], v[28:31]
	global_load_lds_dwordx4 v237, s[60:61]
	v_mfma_f32_16x16x32_bf16 v[24:27], v[132:135], v[156:159], v[24:27]
	v_mfma_f32_16x16x32_bf16 v[20:23], v[136:139], v[156:159], v[20:23]
	v_mfma_f32_16x16x32_bf16 v[16:19], v[140:143], v[156:159], v[16:19]
	ds_read_b128 v[156:159], v188 offset:9216
	ds_read_b128 v[176:179], v192 offset:33792
	v_mfma_f32_16x16x32_bf16 v[12:15], v[128:131], v[152:155], v[12:15]
	v_mfma_f32_16x16x32_bf16 v[8:11], v[132:135], v[152:155], v[8:11]
	v_mfma_f32_16x16x32_bf16 v[4:7], v[136:139], v[152:155], v[4:7]
	v_mfma_f32_16x16x32_bf16 v[0:3], v[140:143], v[152:155], v[0:3]
	ds_read_b128 v[152:155], v188 offset:11264
	ds_read_b128 v[180:183], v192 offset:35840
	s_add_u32 m0, s43, 0xc000
	v_mfma_f32_16x16x32_bf16 v[52:55], v[128:131], v[148:151], v[52:55]
	global_load_lds_dwordx4 v238, s[60:61]
	v_mfma_f32_16x16x32_bf16 v[64:67], v[132:135], v[148:151], v[64:67]
	v_mfma_f32_16x16x32_bf16 v[48:51], v[136:139], v[148:151], v[48:51]
	v_mfma_f32_16x16x32_bf16 v[60:63], v[140:143], v[148:151], v[60:63]
	ds_read_b128 v[148:151], v188 offset:13312
	ds_read_b128 v[184:187], v192 offset:37888
	ds_read_b128 v[188:191], v188 offset:15360
	ds_read_b128 v[192:195], v192 offset:39936
	v_mfma_f32_16x16x32_bf16 v[36:39], v[128:131], v[144:147], v[36:39]
	v_mfma_f32_16x16x32_bf16 v[44:47], v[132:135], v[144:147], v[44:47]
	v_mfma_f32_16x16x32_bf16 v[32:35], v[136:139], v[144:147], v[32:35]
	v_mfma_f32_16x16x32_bf16 v[40:43], v[140:143], v[144:147], v[40:43]
	s_add_u32 s44, s44, 64
	s_addc_u32 s45, s45, 0
	s_add_u32 s60, s60, 64
	s_addc_u32 s61, s61, 0
	s_xor_b32 s42, s42, 0x10000
	v_add_u32_e32 v140, s42, v233
	v_add_u32_e32 v141, s42, v232
	s_waitcnt vmcnt(8)
	s_waitcnt lgkmcnt(0)
	s_barrier
	s_add_u32 m0, s43, 0x400
	v_mfma_f32_16x16x32_bf16 v[124:127], v[176:179], v[172:175], v[124:127]
	global_load_lds_dwordx4 v237, s[44:45]
	v_mfma_f32_16x16x32_bf16 v[120:123], v[180:183], v[172:175], v[120:123]
	v_mfma_f32_16x16x32_bf16 v[116:119], v[184:187], v[172:175], v[116:119]
	v_mfma_f32_16x16x32_bf16 v[112:115], v[192:195], v[172:175], v[112:115]
	ds_read_b128 v[172:175], v140
	v_mfma_f32_16x16x32_bf16 v[108:111], v[176:179], v[168:171], v[108:111]
	v_mfma_f32_16x16x32_bf16 v[104:107], v[180:183], v[168:171], v[104:107]
	v_mfma_f32_16x16x32_bf16 v[100:103], v[184:187], v[168:171], v[100:103]
	v_mfma_f32_16x16x32_bf16 v[96:99], v[192:195], v[168:171], v[96:99]
	ds_read_b128 v[168:171], v140 offset:2048
	s_add_u32 m0, s43, 0x4400
	v_mfma_f32_16x16x32_bf16 v[92:95], v[176:179], v[164:167], v[92:95]
	global_load_lds_dwordx4 v238, s[44:45]
	v_mfma_f32_16x16x32_bf16 v[88:91], v[180:183], v[164:167], v[88:91]
	v_mfma_f32_16x16x32_bf16 v[84:87], v[184:187], v[164:167], v[84:87]
	v_mfma_f32_16x16x32_bf16 v[80:83], v[192:195], v[164:167], v[80:83]
	ds_read_b128 v[164:167], v140 offset:4096
	v_mfma_f32_16x16x32_bf16 v[76:79], v[176:179], v[160:163], v[76:79]
	v_mfma_f32_16x16x32_bf16 v[72:75], v[180:183], v[160:163], v[72:75]
	v_mfma_f32_16x16x32_bf16 v[68:71], v[184:187], v[160:163], v[68:71]
	v_mfma_f32_16x16x32_bf16 v[56:59], v[192:195], v[160:163], v[56:59]
	ds_read_b128 v[160:163], v140 offset:6144
	s_add_u32 m0, s43, 0x8400
	v_mfma_f32_16x16x32_bf16 v[28:31], v[176:179], v[156:159], v[28:31]
	global_load_lds_dwordx4 v237, s[60:61]
	v_mfma_f32_16x16x32_bf16 v[24:27], v[180:183], v[156:159], v[24:27]
	v_mfma_f32_16x16x32_bf16 v[20:23], v[184:187], v[156:159], v[20:23]
	v_mfma_f32_16x16x32_bf16 v[16:19], v[192:195], v[156:159], v[16:19]
	ds_read_b128 v[156:159], v140 offset:8192
	ds_read_b128 v[128:131], v141 offset:32768
	v_mfma_f32_16x16x32_bf16 v[12:15], v[176:179], v[152:155], v[12:15]
	v_mfma_f32_16x16x32_bf16 v[8:11], v[180:183], v[152:155], v[8:11]
	v_mfma_f32_16x16x32_bf16 v[4:7], v[184:187], v[152:155], v[4:7]
	v_mfma_f32_16x16x32_bf16 v[0:3], v[192:195], v[152:155], v[0:3]
	ds_read_b128 v[152:155], v140 offset:10240
	ds_read_b128 v[132:135], v141 offset:34816
	s_add_u32 m0, s43, 0xc400
	v_mfma_f32_16x16x32_bf16 v[52:55], v[176:179], v[148:151], v[52:55]
	global_load_lds_dwordx4 v238, s[60:61]
	v_mfma_f32_16x16x32_bf16 v[64:67], v[180:183], v[148:151], v[64:67]
	v_mfma_f32_16x16x32_bf16 v[48:51], v[184:187], v[148:151], v[48:51]
	v_mfma_f32_16x16x32_bf16 v[60:63], v[192:195], v[148:151], v[60:63]
	ds_read_b128 v[148:151], v140 offset:12288
	ds_read_b128 v[136:139], v141 offset:36864
	ds_read_b128 v[144:147], v140 offset:14336
	ds_read_b128 v[140:143], v141 offset:38912
	v_mfma_f32_16x16x32_bf16 v[36:39], v[176:179], v[188:191], v[36:39]
	v_mfma_f32_16x16x32_bf16 v[44:47], v[180:183], v[188:191], v[44:47]
	v_mfma_f32_16x16x32_bf16 v[32:35], v[184:187], v[188:191], v[32:35]
	v_mfma_f32_16x16x32_bf16 v[40:43], v[192:195], v[188:191], v[40:43]
	s_add_i32 s24, s24, 0x10000
	s_add_u32 s22, s22, 0x80
	s_addc_u32 s23, s23, 0
	s_add_i32 s25, s25, 1
	s_and_b32 s42, s24, 0x10000
	s_add_u32 s44, s20, s22
	s_addc_u32 s45, s21, s23
	s_add_u32 s60, s18, s22
	s_addc_u32 s61, s19, s23
	s_add_i32 s43, s46, s42
	v_add_u32_e32 v188, s42, v233
	v_or_b32_e32 v192, s42, v232
	s_cmp_lt_u32 s25, s31
	s_waitcnt vmcnt(8)
	s_waitcnt lgkmcnt(0)
	s_barrier
	s_cbranch_scc1 .Lg_ld_A
	s_branch .LBB0_656
